# attention work queue: the first unit of each workgroup is its block index (no start-of-phase atomic storm), later pops add the grid size
# speedup vs baseline: 1.0018x; 1.0018x over previous
; template <int MODE> __device__ __forceinline__ void attn_unit4(LAS unsigned char* lds, const int uidx, const AttnArgs& A) {
;     ...
;             const float sx = wave_sum(A.dl[lane] * A.dl[64 + lane], lane), sy = wave_sum(A.dl[128 + lane] * A.dl[192 + lane], lane);
;             const float lam = __expf(sx) - __expf(sy) + A.lam_init;
; __global__ void __launch_bounds__(NTHR, 2) mega_fwd(KArgs a) {
;     ...
;             AttnArgs A{U, KC, VC, (bf16_t*)(ws + WS_O), a.in[3], a.in[9] + (size_t)l * 256, a.in[10] + (size_t)l * 128, a.in[11] + (size_t)l * 4, 0.8f - 0.6f * __expf(-0.3f * (float)l)};
;             constexpr int NA = NSEQ * 4 * 65, NC = NSEQ * 2 * 65, NB = NSEQ * 2 * 65;
;             unsigned* qhead = (unsigned*)ws + CW_QUEUE + 64 * l;
;             for (;;) {
;                 if (threadIdx.x == 0) MISC[16] = atomicAdd(qhead, 1u);
;                 __syncthreads();
;                 const int u = (int)MISC[16];
.LBB0_907:
	s_or_b64 exec, exec, s[0:1]
	v_readlane_b32 s0, v254, 62
	s_add_u32 s10, s20, 0x2ea00000
	v_readlane_b32 s1, v254, 63
	v_readlane_b32 s68, v254, 33
	s_addc_u32 s11, s21, 0
	s_lshl_b64 s[0:1], s[0:1], 2
	v_readlane_b32 s76, v254, 41
	v_readlane_b32 s77, v254, 42
	s_add_u32 s0, s76, s0
	s_addc_u32 s1, s77, s1
	v_readlane_b32 s69, v254, 34
	v_readlane_b32 s70, v254, 35
	v_readlane_b32 s71, v254, 36
	v_readlane_b32 s72, v254, 37
	v_readlane_b32 s73, v254, 38
	v_readlane_b32 s74, v254, 39
	v_readlane_b32 s75, v254, 40
	v_readlane_b32 s78, v254, 43
	v_readlane_b32 s79, v254, 44
	v_readlane_b32 s80, v254, 45
	v_readlane_b32 s81, v254, 46
	v_readlane_b32 s82, v254, 47
	v_readlane_b32 s83, v254, 48
	v_writelane_b32 v254, s0, 62
	s_waitcnt lgkmcnt(0)
	v_mov_b32_e32 v2, 0x3f4ccccd
	v_writelane_b32 v254, s1, 63
	s_barrier
	v_readlane_b32 s0, v254, 59
	v_readlane_b32 s1, v254, 60
	v_readlane_b32 s4, v254, 55
	s_lshl_b64 s[0:1], s[0:1], 2
	v_readlane_b32 s5, v254, 56
	s_add_u32 s60, s78, s0
	v_cvt_f32_u32_e32 v0, s4
	s_addc_u32 s61, s79, s1
	s_lshl_b64 s[0:1], s[4:5], 4
	s_add_u32 s68, s80, s0
	s_addc_u32 s89, s81, s1
	s_lshl_b32 s30, s4, 6
	s_lshl_b64 s[0:1], s[30:31], 2
	v_mul_f32_e32 v0, 0xbe99999a, v0
	s_add_u32 s20, s20, s0
	v_mul_f32_e32 v0, 0x3fb8aa3b, v0
	s_addc_u32 s21, s21, s1
	v_exp_f32_e32 v0, v0
	s_cmp_eq_u32 s4, 1
	s_cselect_b64 s[82:83], -1, 0
	s_add_u32 s0, s16, 0x1000
	v_writelane_b32 v254, s0, 59
	s_addc_u32 s0, s17, 0
	v_writelane_b32 v255, s0, 0
	s_add_u32 s0, s16, 0x4df00
	v_fmamk_f32 v189, v0, 0xbf19999a, v2
	v_writelane_b32 v254, s0, 61
	s_addc_u32 s0, s17, 0
	v_sub_f32_e32 v191, 1.0, v189
	v_writelane_b32 v255, s0, 2
	v_readlane_b32 s84, v254, 62
	v_readlane_b32 s85, v254, 63
	v_and_b32_e32 v228, 63, v252
	v_lshlrev_b32_e32 v228, 2, v228
	s_nop 4
	global_load_dword v229, v228, s[84:85]
	global_load_dword v230, v228, s[84:85] offset:256
	global_load_dword v231, v228, s[84:85] offset:512
	global_load_dword v232, v228, s[84:85] offset:768
	s_waitcnt vmcnt(0)
	v_mul_f32_e32 v233, v229, v230
	v_xor_b32_e32 v234, 4, v228
	ds_bpermute_b32 v234, v234, v233
	s_waitcnt lgkmcnt(0)
	v_fmac_f32_e32 v234, v229, v230
	v_xor_b32_e32 v233, 8, v228
	ds_bpermute_b32 v233, v233, v234
	s_waitcnt lgkmcnt(0)
	v_add_f32_e32 v234, v234, v233
	v_xor_b32_e32 v233, 16, v228
	ds_bpermute_b32 v233, v233, v234
	s_waitcnt lgkmcnt(0)
	v_add_f32_e32 v234, v234, v233
	v_xor_b32_e32 v233, 32, v228
	ds_bpermute_b32 v233, v233, v234
	s_waitcnt lgkmcnt(0)
	v_add_f32_e32 v234, v234, v233
	v_xor_b32_e32 v233, 64, v228
	ds_bpermute_b32 v233, v233, v234
	s_waitcnt lgkmcnt(0)
	v_add_f32_e32 v234, v234, v233
	v_xor_b32_e32 v233, 0x80, v228
	ds_bpermute_b32 v233, v233, v234
	s_waitcnt lgkmcnt(0)
	v_add_f32_e32 v234, v234, v233
	v_mul_f32_e32 v234, 0x3fb8aa3b, v234
	v_exp_f32_e32 v235, v234
	v_mul_f32_e32 v233, v231, v232
	v_xor_b32_e32 v236, 4, v228
	ds_bpermute_b32 v236, v236, v233
	s_waitcnt lgkmcnt(0)
	v_fmac_f32_e32 v236, v231, v232
	v_xor_b32_e32 v233, 8, v228
	ds_bpermute_b32 v233, v233, v236
	s_waitcnt lgkmcnt(0)
	v_add_f32_e32 v236, v236, v233
	v_xor_b32_e32 v233, 16, v228
	ds_bpermute_b32 v233, v233, v236
	s_waitcnt lgkmcnt(0)
	v_add_f32_e32 v236, v236, v233
	v_xor_b32_e32 v233, 32, v228
	ds_bpermute_b32 v233, v233, v236
	s_waitcnt lgkmcnt(0)
	v_add_f32_e32 v236, v236, v233
	v_xor_b32_e32 v233, 64, v228
	ds_bpermute_b32 v233, v233, v236
	s_waitcnt lgkmcnt(0)
	v_add_f32_e32 v236, v236, v233
	v_xor_b32_e32 v233, 0x80, v228
	ds_bpermute_b32 v233, v233, v236
	s_waitcnt lgkmcnt(0)
	v_add_f32_e32 v236, v236, v233
	v_mul_f32_e32 v236, 0x3fb8aa3b, v236
	v_exp_f32_e32 v236, v236
	s_nop 0
	v_sub_f32_e32 v236, v235, v236
	v_add_f32_e32 v251, v189, v236
	s_mov_b64 s[76:77], exec
	v_readlane_b32 s78, v253, 4
	v_readlane_b32 s79, v253, 5
	s_and_b64 s[78:79], s[76:77], s[78:79]
	s_mov_b64 exec, s[78:79]
	s_cbranch_execz .Lpf_init
	s_sub_i32 s78, s2, s34
	v_mov_b32_e32 v249, s78

; __global__ void __launch_bounds__(NTHR, 2) mega_fwd(KArgs a) {
;     ...
;                 if (threadIdx.x == 0) MISC[16] = atomicAdd(qhead, 1u);
;                 __syncthreads();
;                 const int u = (int)MISC[16];
;                 __syncthreads();
;                 if (u >= NA + NC + NB) break;
;                 if (l == 1 && (u % 65) == 0) continue;
;                 if (u < NA) ATTN_FN<0>(lds, u, A);
;                 else if (u < NA + NC) ATTN_FN<1>(lds, u - NA, A);
;                 else ATTN_FN<2>(lds, u - NA - NC, A);
.LBB0_914:
	s_or_b64 exec, exec, s[0:1]
	v_readlane_b32 s0, v254, 10
	s_waitcnt lgkmcnt(0)
	s_barrier
	v_mov_b32_e32 v0, s0
	ds_read_b32 v0, v0
	s_movk_i32 s0, 0x144f
	s_waitcnt lgkmcnt(0)
	s_barrier
	v_readfirstlane_b32 s36, v0
	s_add_i32 s36, s36, s34
	s_cmpk_gt_i32 s36, 0x144f
	s_cselect_b64 vcc, -1, 0
	s_mov_b64 s[0:1], -1
	s_cbranch_vccnz .LBB0_911
	s_mul_hi_i32 s53, s36, 0x7e07e07f
	s_lshr_b32 s64, s53, 31
	s_ashr_i32 s37, s53, 5
	s_add_i32 s37, s37, s64
	s_mul_i32 s0, s37, 0x41
	s_sub_i32 s52, s36, s0
	s_cmp_eq_u32 s52, 0
	s_cselect_b64 s[0:1], -1, 0
	s_and_b64 s[0:1], s[82:83], s[0:1]
	s_and_b64 vcc, exec, s[0:1]
	s_cbranch_vccnz .Lpf_cont_stub
	s_cmpk_gt_i32 s36, 0xa27
	s_mov_b64 s[0:1], -1
	s_cbranch_scc0 .LBB0_970
	s_cmpk_gt_u32 s36, 0xf3b
	s_cbranch_scc0 .LBB0_954
	v_mov_b32_e32 v2, v252
	v_mov_b32_e32 v44, 0xf149f2ca
	v_add_u32_e32 v0, 0xffffff00, v2
	v_sub_u32_e32 v3, 0x100, v2
	v_max_i32_e32 v0, v0, v3
	v_readfirstlane_b32 s15, v2
	v_cmp_lt_u32_e32 vcc, 7, v0
	s_and_saveexec_b64 s[0:1], vcc
	s_cbranch_execz .LBB0_926
	v_cmp_lt_u32_e32 vcc, 11, v0
	v_mov_b32_e32 v3, 8
	s_and_saveexec_b64 s[4:5], vcc
	s_cbranch_execz .LBB0_925
	v_cmp_lt_u32_e32 vcc, 15, v0
	v_mov_b32_e32 v3, 9
	s_and_saveexec_b64 s[6:7], vcc
	s_cbranch_execz .LBB0_924
	v_cmp_lt_u32_e32 vcc, 22, v0
	v_mov_b32_e32 v3, 10
	s_and_saveexec_b64 s[8:9], vcc
	s_movk_i32 s14, 0x5b
	v_cmp_gt_u32_e32 vcc, s14, v0
	s_nop 1
	v_cndmask_b32_e64 v3, 15, 14, vcc
	v_cmp_lt_u32_e32 vcc, 63, v0
	s_nop 1
	v_cndmask_b32_e32 v3, 13, v3, vcc
	v_cmp_lt_u32_e32 vcc, 45, v0
	s_nop 1
	v_cndmask_b32_e32 v3, 12, v3, vcc
	v_cmp_lt_u32_e32 vcc, 31, v0
	s_nop 1
	v_cndmask_b32_e32 v3, 11, v3, vcc
	s_or_b64 exec, exec, s[8:9]
